# convert_layer (phase ln1): the four serialized tile loads of four convert_tile variants issued together, on top of v20
# baseline (speedup 1.0000x reference)
.LBB0_902:
	s_cmpk_gt_i32 s33, 0x91f
	s_mov_b64 s[14:15], -1
	s_cbranch_scc0 .LBB0_920
	s_cmpk_gt_u32 s33, 0xb1f
	s_cbranch_scc0 .LBB0_917
	s_cmpk_gt_u32 s33, 0xc1f
	s_cbranch_scc0 .LBB0_914
	s_cmpk_gt_u32 s33, 0xd1f
	s_cbranch_scc0 .LBB0_911
	s_cmpk_gt_u32 s33, 0x129f
	s_cbranch_scc0 .LBB0_908
	s_add_i32 s14, s33, 0xed60
	s_and_b32 s15, s14, 0xffff
	s_mul_i32 s15, s15, 0xba2f
	s_lshr_b32 s15, s15, 21
	s_mul_i32 s16, s15, 44
	s_sub_i32 s16, s14, s16
	v_mov_b32_e32 v8, v244
	s_lshl_b32 s14, s15, 6
	v_lshlrev_b32_e32 v0, 2, v8
	s_lshl_b32 s15, s16, 6
	v_and_b32_e32 v2, 60, v0
	v_ashrrev_i32_e32 v3, 4, v8
	s_and_b32 s15, s15, 0xffc0
	v_or_b32_e32 v0, s14, v2
	v_add_u32_e32 v6, s15, v3
	v_lshlrev_b32_e32 v0, 2, v0
	v_mov_b32_e32 v1, v96
	v_ashrrev_i32_e32 v7, 31, v6
	v_lshl_add_u64 v[4:5], s[0:1], 0, v[0:1]
	v_lshlrev_b64 v[0:1], 12, v[6:7]
	s_movk_i32 s50, 0x104
	v_lshl_add_u64 v[0:1], v[4:5], 0, v[0:1]
	v_mul_lo_u32 v3, v3, s50
	s_barrier
	v_lshl_add_u32 v7, v2, 2, v3
	global_load_dwordx4 v[100:103], v[0:1], off
	v_add_u32_e32 v122, 16, v6
	v_ashrrev_i32_e32 v123, 31, v122
	v_lshlrev_b64 v[122:123], 12, v[122:123]
	v_lshl_add_u64 v[122:123], v[4:5], 0, v[122:123]
	global_load_dwordx4 v[104:107], v[122:123], off
	v_add_u32_e32 v124, 32, v6
	v_ashrrev_i32_e32 v125, 31, v124
	v_lshlrev_b64 v[124:125], 12, v[124:125]
	v_lshl_add_u64 v[124:125], v[4:5], 0, v[124:125]
	global_load_dwordx4 v[108:111], v[124:125], off
	v_add_u32_e32 v126, 48, v6
	v_ashrrev_i32_e32 v127, 31, v126
	v_lshlrev_b64 v[126:127], 12, v[126:127]
	v_lshl_add_u64 v[126:127], v[4:5], 0, v[126:127]
	global_load_dwordx4 v[112:115], v[126:127], off
	v_add_u32_e32 v9, 0x1040, v7
	s_lshl_b32 s15, s15, 1
	s_add_u32 s16, s34, s15
	s_addc_u32 s17, s35, 0
	v_ashrrev_i32_e32 v10, 3, v8
	s_movk_i32 s15, 0x1600
	s_waitcnt vmcnt(3)
	ds_write2_b32 v7, v100, v101 offset1:1
	ds_write2_b32 v7, v102, v103 offset0:2 offset1:3
	s_waitcnt vmcnt(2)
	ds_write2_b32 v9, v104, v105 offset1:1
	v_add_u32_e32 v0, 0x1048, v7
	ds_write2_b32 v0, v106, v107 offset1:1
	v_add_u32_e32 v9, 0x2080, v7
	s_waitcnt vmcnt(1)
	ds_write2_b32 v9, v108, v109 offset1:1
	v_add_u32_e32 v0, 0x2088, v7
	ds_write2_b32 v0, v110, v111 offset1:1
	v_add_u32_e32 v4, 0x30c0, v7
	s_waitcnt vmcnt(0)
	ds_write2_b32 v4, v112, v113 offset1:1
	v_add_u32_e32 v0, 0x30c8, v7
	ds_write2_b32 v0, v114, v115 offset1:1
	v_lshlrev_b32_e32 v0, 3, v8
	v_and_b32_e32 v9, 56, v0
	v_lshlrev_b32_e32 v0, 1, v9
	v_mov_b32_e32 v1, v96
	v_lshl_add_u64 v[4:5], s[16:17], 0, v[0:1]
	v_lshlrev_b32_e32 v0, 2, v10
	v_mad_u32_u24 v6, v9, s50, v0
	s_waitcnt lgkmcnt(0)
	s_barrier
	ds_read2_b32 v[0:1], v6 offset1:65
	ds_read2_b32 v[2:3], v6 offset0:130 offset1:195
	v_add_u32_e32 v6, 0x400, v6
	s_waitcnt lgkmcnt(1)
	v_cvt_pk_bf16_f32 v0, v0, v1
	s_nop 1
	s_waitcnt lgkmcnt(0)
	v_cvt_pk_bf16_f32 v1, v2, v3
	s_nop 1
	ds_read2_b32 v[2:3], v6 offset0:4 offset1:69
	ds_read2_b32 v[6:7], v6 offset0:134 offset1:199
	s_waitcnt lgkmcnt(1)
	v_cvt_pk_bf16_f32 v2, v2, v3
	s_nop 1
	s_waitcnt lgkmcnt(0)
	v_cvt_pk_bf16_f32 v3, v6, v7
	s_nop 1
	v_add_u32_e32 v6, s14, v10
	v_mad_i64_i32 v[6:7], s[16:17], v6, s15, v[4:5]
	global_store_dwordx4 v[6:7], v[0:3], off
	s_nop 1
	v_add_u32_e32 v0, 0x100, v8
	v_ashrrev_i32_e32 v6, 3, v0
	v_lshlrev_b32_e32 v0, 2, v6
	v_mad_u32_u24 v2, v9, s50, v0
	ds_read2_b32 v[0:1], v2 offset1:65
	v_add_u32_e32 v8, 0x400, v2
	s_waitcnt lgkmcnt(0)
	v_cvt_pk_bf16_f32 v7, v0, v1
	s_nop 1
	ds_read2_b32 v[0:1], v2 offset0:130 offset1:195
	ds_read2_b32 v[2:3], v8 offset0:4 offset1:69
	s_waitcnt lgkmcnt(1)
	v_cvt_pk_bf16_f32 v0, v0, v1
	s_nop 1
	s_waitcnt lgkmcnt(0)
	v_cvt_pk_bf16_f32 v1, v2, v3
	s_nop 1
	ds_read2_b32 v[2:3], v8 offset0:134 offset1:199
	s_waitcnt lgkmcnt(0)
	v_cvt_pk_bf16_f32 v2, v2, v3
	s_nop 1
	v_add_u32_e32 v3, s14, v6
	v_mad_i64_i32 v[4:5], s[14:15], v3, s15, v[4:5]
	global_store_dword v[4:5], v7, off
	s_mov_b64 s[14:15], 0

.LBB0_911:
	s_andn2_b64 vcc, exec, s[14:15]
	s_cbranch_vccnz .LBB0_913
	v_mov_b32_e32 v8, v244
	s_and_b32 s14, s47, 0x3fc0
	v_lshlrev_b32_e32 v0, 2, v8
	v_ashrrev_i32_e32 v3, 4, v8
	s_and_b32 s15, s2, 0x3c0
	v_and_b32_e32 v2, 60, v0
	s_addk_i32 s14, 0xcf80
	v_add_u32_e32 v6, s15, v3
	v_or_b32_e32 v0, s14, v2
	v_mov_b32_e32 v1, v96
	v_ashrrev_i32_e32 v7, 31, v6
	v_lshl_add_u64 v[4:5], v[0:1], 2, s[8:9]
	v_lshlrev_b64 v[0:1], 12, v[6:7]
	s_movk_i32 s50, 0x104
	v_lshl_add_u64 v[0:1], v[4:5], 0, v[0:1]
	v_mul_lo_u32 v3, v3, s50
	s_barrier
	v_lshl_add_u32 v7, v2, 2, v3
	global_load_dwordx4 v[100:103], v[0:1], off
	v_add_u32_e32 v122, 16, v6
	v_ashrrev_i32_e32 v123, 31, v122
	v_lshlrev_b64 v[122:123], 12, v[122:123]
	v_lshl_add_u64 v[122:123], v[4:5], 0, v[122:123]
	global_load_dwordx4 v[104:107], v[122:123], off
	v_add_u32_e32 v124, 32, v6
	v_ashrrev_i32_e32 v125, 31, v124
	v_lshlrev_b64 v[124:125], 12, v[124:125]
	v_lshl_add_u64 v[124:125], v[4:5], 0, v[124:125]
	global_load_dwordx4 v[108:111], v[124:125], off
	v_add_u32_e32 v126, 48, v6
	v_ashrrev_i32_e32 v127, 31, v126
	v_lshlrev_b64 v[126:127], 12, v[126:127]
	v_lshl_add_u64 v[126:127], v[4:5], 0, v[126:127]
	global_load_dwordx4 v[112:115], v[126:127], off
	v_add_u32_e32 v9, 0x1040, v7
	s_lshl_b32 s15, s15, 1
	s_add_u32 s16, s38, s15
	s_addc_u32 s17, s39, 0
	v_ashrrev_i32_e32 v10, 3, v8
	s_waitcnt vmcnt(3)
	ds_write2_b32 v7, v100, v101 offset1:1
	ds_write2_b32 v7, v102, v103 offset0:2 offset1:3
	s_waitcnt vmcnt(2)
	ds_write2_b32 v9, v104, v105 offset1:1
	v_add_u32_e32 v0, 0x1048, v7
	ds_write2_b32 v0, v106, v107 offset1:1
	v_add_u32_e32 v9, 0x2080, v7
	s_waitcnt vmcnt(1)
	ds_write2_b32 v9, v108, v109 offset1:1
	v_add_u32_e32 v0, 0x2088, v7
	ds_write2_b32 v0, v110, v111 offset1:1
	v_add_u32_e32 v4, 0x30c0, v7
	s_waitcnt vmcnt(0)
	ds_write2_b32 v4, v112, v113 offset1:1
	v_add_u32_e32 v0, 0x30c8, v7
	ds_write2_b32 v0, v114, v115 offset1:1
	v_lshlrev_b32_e32 v0, 3, v8
	v_and_b32_e32 v9, 56, v0
	v_lshlrev_b32_e32 v0, 1, v9
	v_mov_b32_e32 v1, v96
	v_lshl_add_u64 v[4:5], s[16:17], 0, v[0:1]
	v_lshlrev_b32_e32 v0, 2, v10
	v_mad_u32_u24 v6, v9, s50, v0
	s_waitcnt lgkmcnt(0)
	s_barrier
	ds_read2_b32 v[0:1], v6 offset1:65
	ds_read2_b32 v[2:3], v6 offset0:130 offset1:195
	v_add_u32_e32 v6, 0x400, v6
	s_waitcnt lgkmcnt(1)
	v_cvt_pk_bf16_f32 v0, v0, v1
	s_nop 1
	s_waitcnt lgkmcnt(0)
	v_cvt_pk_bf16_f32 v1, v2, v3
	s_nop 1
	ds_read2_b32 v[2:3], v6 offset0:4 offset1:69
	ds_read2_b32 v[6:7], v6 offset0:134 offset1:199
	s_waitcnt lgkmcnt(1)
	v_cvt_pk_bf16_f32 v2, v2, v3
	s_nop 1
	s_waitcnt lgkmcnt(0)
	v_cvt_pk_bf16_f32 v3, v6, v7
	s_nop 1
	v_add_u32_e32 v6, s14, v10
	v_ashrrev_i32_e32 v7, 31, v6
	v_lshlrev_b64 v[6:7], 11, v[6:7]
	v_lshl_add_u64 v[6:7], v[4:5], 0, v[6:7]
	global_store_dwordx4 v[6:7], v[0:3], off
	s_nop 1
	v_add_u32_e32 v0, 0x100, v8
	v_ashrrev_i32_e32 v6, 3, v0
	v_lshlrev_b32_e32 v0, 2, v6
	v_mad_u32_u24 v2, v9, s50, v0
	ds_read2_b32 v[0:1], v2 offset1:65
	v_add_u32_e32 v7, 0x400, v2
	s_waitcnt lgkmcnt(0)
	v_cvt_pk_bf16_f32 v8, v0, v1
	s_nop 1
	ds_read2_b32 v[0:1], v2 offset0:130 offset1:195
	ds_read2_b32 v[2:3], v7 offset0:4 offset1:69
	v_add_u32_e32 v6, s14, v6
	s_waitcnt lgkmcnt(1)
	v_cvt_pk_bf16_f32 v0, v0, v1
	s_nop 1
	s_waitcnt lgkmcnt(0)
	v_cvt_pk_bf16_f32 v1, v2, v3
	s_nop 1
	ds_read2_b32 v[2:3], v7 offset0:134 offset1:199
	v_ashrrev_i32_e32 v7, 31, v6
	v_lshlrev_b64 v[6:7], 11, v[6:7]
	v_lshl_add_u64 v[4:5], v[4:5], 0, v[6:7]
	s_waitcnt lgkmcnt(0)
	v_cvt_pk_bf16_f32 v2, v2, v3
	s_nop 1
	global_store_dword v[4:5], v8, off

.LBB0_914:
	s_andn2_b64 vcc, exec, s[14:15]
	s_cbranch_vccnz .LBB0_916
	v_mov_b32_e32 v8, v244
	s_and_b32 s14, s47, 0x3fc0
	v_lshlrev_b32_e32 v0, 2, v8
	v_ashrrev_i32_e32 v3, 4, v8
	s_and_b32 s15, s2, 0x3c0
	v_and_b32_e32 v2, 60, v0
	s_addk_i32 s14, 0xd380
	v_add_u32_e32 v6, s15, v3
	v_or_b32_e32 v0, s14, v2
	v_mov_b32_e32 v1, v96
	v_ashrrev_i32_e32 v7, 31, v6
	v_lshl_add_u64 v[4:5], v[0:1], 2, s[6:7]
	v_lshlrev_b64 v[0:1], 12, v[6:7]
	s_movk_i32 s50, 0x104
	v_lshl_add_u64 v[0:1], v[4:5], 0, v[0:1]
	v_mul_lo_u32 v3, v3, s50
	s_barrier
	v_lshl_add_u32 v7, v2, 2, v3
	global_load_dwordx4 v[100:103], v[0:1], off
	v_add_u32_e32 v122, 16, v6
	v_ashrrev_i32_e32 v123, 31, v122
	v_lshlrev_b64 v[122:123], 12, v[122:123]
	v_lshl_add_u64 v[122:123], v[4:5], 0, v[122:123]
	global_load_dwordx4 v[104:107], v[122:123], off
	v_add_u32_e32 v124, 32, v6
	v_ashrrev_i32_e32 v125, 31, v124
	v_lshlrev_b64 v[124:125], 12, v[124:125]
	v_lshl_add_u64 v[124:125], v[4:5], 0, v[124:125]
	global_load_dwordx4 v[108:111], v[124:125], off
	v_add_u32_e32 v126, 48, v6
	v_ashrrev_i32_e32 v127, 31, v126
	v_lshlrev_b64 v[126:127], 12, v[126:127]
	v_lshl_add_u64 v[126:127], v[4:5], 0, v[126:127]
	global_load_dwordx4 v[112:115], v[126:127], off
	v_add_u32_e32 v9, 0x1040, v7
	s_lshl_b32 s15, s15, 1
	s_add_u32 s16, s42, s15
	s_addc_u32 s17, s43, 0
	v_ashrrev_i32_e32 v10, 3, v8
	s_waitcnt vmcnt(3)
	ds_write2_b32 v7, v100, v101 offset1:1
	ds_write2_b32 v7, v102, v103 offset0:2 offset1:3
	s_waitcnt vmcnt(2)
	ds_write2_b32 v9, v104, v105 offset1:1
	v_add_u32_e32 v0, 0x1048, v7
	ds_write2_b32 v0, v106, v107 offset1:1
	v_add_u32_e32 v9, 0x2080, v7
	s_waitcnt vmcnt(1)
	ds_write2_b32 v9, v108, v109 offset1:1
	v_add_u32_e32 v0, 0x2088, v7
	ds_write2_b32 v0, v110, v111 offset1:1
	v_add_u32_e32 v4, 0x30c0, v7
	s_waitcnt vmcnt(0)
	ds_write2_b32 v4, v112, v113 offset1:1
	v_add_u32_e32 v0, 0x30c8, v7
	ds_write2_b32 v0, v114, v115 offset1:1
	v_lshlrev_b32_e32 v0, 3, v8
	v_and_b32_e32 v9, 56, v0
	v_lshlrev_b32_e32 v0, 1, v9
	v_mov_b32_e32 v1, v96
	v_lshl_add_u64 v[4:5], s[16:17], 0, v[0:1]
	v_lshlrev_b32_e32 v0, 2, v10
	v_mad_u32_u24 v6, v9, s50, v0
	s_waitcnt lgkmcnt(0)
	s_barrier
	ds_read2_b32 v[0:1], v6 offset1:65
	ds_read2_b32 v[2:3], v6 offset0:130 offset1:195
	v_add_u32_e32 v6, 0x400, v6
	s_waitcnt lgkmcnt(1)
	v_cvt_pk_bf16_f32 v0, v0, v1
	s_nop 1
	s_waitcnt lgkmcnt(0)
	v_cvt_pk_bf16_f32 v1, v2, v3
	s_nop 1
	ds_read2_b32 v[2:3], v6 offset0:4 offset1:69
	ds_read2_b32 v[6:7], v6 offset0:134 offset1:199
	s_waitcnt lgkmcnt(1)
	v_cvt_pk_bf16_f32 v2, v2, v3
	s_nop 1
	s_waitcnt lgkmcnt(0)
	v_cvt_pk_bf16_f32 v3, v6, v7
	s_nop 1
	v_add_u32_e32 v6, s14, v10
	v_ashrrev_i32_e32 v7, 31, v6
	v_lshlrev_b64 v[6:7], 11, v[6:7]
	v_lshl_add_u64 v[6:7], v[4:5], 0, v[6:7]
	global_store_dwordx4 v[6:7], v[0:3], off
	s_nop 1
	v_add_u32_e32 v0, 0x100, v8
	v_ashrrev_i32_e32 v6, 3, v0
	v_lshlrev_b32_e32 v0, 2, v6
	v_mad_u32_u24 v2, v9, s50, v0
	ds_read2_b32 v[0:1], v2 offset1:65
	v_add_u32_e32 v7, 0x400, v2
	s_waitcnt lgkmcnt(0)
	v_cvt_pk_bf16_f32 v8, v0, v1
	s_nop 1
	ds_read2_b32 v[0:1], v2 offset0:130 offset1:195
	ds_read2_b32 v[2:3], v7 offset0:4 offset1:69
	v_add_u32_e32 v6, s14, v6
	s_waitcnt lgkmcnt(1)
	v_cvt_pk_bf16_f32 v0, v0, v1
	s_nop 1
	s_waitcnt lgkmcnt(0)
	v_cvt_pk_bf16_f32 v1, v2, v3
	s_nop 1
	ds_read2_b32 v[2:3], v7 offset0:134 offset1:199
	v_ashrrev_i32_e32 v7, 31, v6
	v_lshlrev_b64 v[6:7], 11, v[6:7]
	v_lshl_add_u64 v[4:5], v[4:5], 0, v[6:7]
	s_waitcnt lgkmcnt(0)
	v_cvt_pk_bf16_f32 v2, v2, v3
	s_nop 1
	global_store_dword v[4:5], v8, off

.LBB0_917:
	s_andn2_b64 vcc, exec, s[14:15]
	s_cbranch_vccnz .LBB0_919
	v_mov_b32_e32 v8, v244
	s_and_b32 s14, s48, 0x1fc0
	v_lshlrev_b32_e32 v0, 2, v8
	v_ashrrev_i32_e32 v3, 4, v8
	s_and_b32 s15, s2, 0x7c0
	v_and_b32_e32 v2, 60, v0
	s_addk_i32 s14, 0xedc0
	v_add_u32_e32 v6, s15, v3
	v_or_b32_e32 v0, s14, v2
	v_mov_b32_e32 v1, v96
	v_ashrrev_i32_e32 v7, 31, v6
	v_lshl_add_u64 v[4:5], v[0:1], 2, s[4:5]
	v_lshlrev_b64 v[0:1], 12, v[6:7]
	s_movk_i32 s50, 0x104
	v_lshl_add_u64 v[0:1], v[4:5], 0, v[0:1]
	v_mul_lo_u32 v3, v3, s50
	s_barrier
	v_lshl_add_u32 v7, v2, 2, v3
	global_load_dwordx4 v[100:103], v[0:1], off
	v_add_u32_e32 v122, 16, v6
	v_ashrrev_i32_e32 v123, 31, v122
	v_lshlrev_b64 v[122:123], 12, v[122:123]
	v_lshl_add_u64 v[122:123], v[4:5], 0, v[122:123]
	global_load_dwordx4 v[104:107], v[122:123], off
	v_add_u32_e32 v124, 32, v6
	v_ashrrev_i32_e32 v125, 31, v124
	v_lshlrev_b64 v[124:125], 12, v[124:125]
	v_lshl_add_u64 v[124:125], v[4:5], 0, v[124:125]
	global_load_dwordx4 v[108:111], v[124:125], off
	v_add_u32_e32 v126, 48, v6
	v_ashrrev_i32_e32 v127, 31, v126
	v_lshlrev_b64 v[126:127], 12, v[126:127]
	v_lshl_add_u64 v[126:127], v[4:5], 0, v[126:127]
	global_load_dwordx4 v[112:115], v[126:127], off
	v_add_u32_e32 v9, 0x1040, v7
	s_lshl_b32 s15, s15, 1
	s_add_u32 s16, s44, s15
	s_addc_u32 s17, s45, 0
	v_ashrrev_i32_e32 v10, 3, v8
	s_waitcnt vmcnt(3)
	ds_write2_b32 v7, v100, v101 offset1:1
	ds_write2_b32 v7, v102, v103 offset0:2 offset1:3
	s_waitcnt vmcnt(2)
	ds_write2_b32 v9, v104, v105 offset1:1
	v_add_u32_e32 v0, 0x1048, v7
	ds_write2_b32 v0, v106, v107 offset1:1
	v_add_u32_e32 v9, 0x2080, v7
	s_waitcnt vmcnt(1)
	ds_write2_b32 v9, v108, v109 offset1:1
	v_add_u32_e32 v0, 0x2088, v7
	ds_write2_b32 v0, v110, v111 offset1:1
	v_add_u32_e32 v4, 0x30c0, v7
	s_waitcnt vmcnt(0)
	ds_write2_b32 v4, v112, v113 offset1:1
	v_add_u32_e32 v0, 0x30c8, v7
	ds_write2_b32 v0, v114, v115 offset1:1
	v_lshlrev_b32_e32 v0, 3, v8
	v_and_b32_e32 v9, 56, v0
	v_lshlrev_b32_e32 v0, 1, v9
	v_mov_b32_e32 v1, v96
	v_lshl_add_u64 v[4:5], s[16:17], 0, v[0:1]
	v_lshlrev_b32_e32 v0, 2, v10
	v_mad_u32_u24 v6, v9, s50, v0
	s_waitcnt lgkmcnt(0)
	s_barrier
	ds_read2_b32 v[0:1], v6 offset1:65
	ds_read2_b32 v[2:3], v6 offset0:130 offset1:195
	v_add_u32_e32 v6, 0x400, v6
	s_waitcnt lgkmcnt(1)
	v_cvt_pk_bf16_f32 v0, v0, v1
	s_nop 1
	s_waitcnt lgkmcnt(0)
	v_cvt_pk_bf16_f32 v1, v2, v3
	s_nop 1
	ds_read2_b32 v[2:3], v6 offset0:4 offset1:69
	ds_read2_b32 v[6:7], v6 offset0:134 offset1:199
	s_waitcnt lgkmcnt(1)
	v_cvt_pk_bf16_f32 v2, v2, v3
	s_nop 1
	s_waitcnt lgkmcnt(0)
	v_cvt_pk_bf16_f32 v3, v6, v7
	s_nop 1
	v_add_u32_e32 v6, s14, v10
	v_ashrrev_i32_e32 v7, 31, v6
	v_lshlrev_b64 v[6:7], 12, v[6:7]
	v_lshl_add_u64 v[6:7], v[4:5], 0, v[6:7]
	global_store_dwordx4 v[6:7], v[0:3], off
	s_nop 1
	v_add_u32_e32 v0, 0x100, v8
	v_ashrrev_i32_e32 v6, 3, v0
	v_lshlrev_b32_e32 v0, 2, v6
	v_mad_u32_u24 v2, v9, s50, v0
	ds_read2_b32 v[0:1], v2 offset1:65
	v_add_u32_e32 v7, 0x400, v2
	s_waitcnt lgkmcnt(0)
	v_cvt_pk_bf16_f32 v8, v0, v1
	s_nop 1
	ds_read2_b32 v[0:1], v2 offset0:130 offset1:195
	ds_read2_b32 v[2:3], v7 offset0:4 offset1:69
	v_add_u32_e32 v6, s14, v6
	s_waitcnt lgkmcnt(1)
	v_cvt_pk_bf16_f32 v0, v0, v1
	s_nop 1
	s_waitcnt lgkmcnt(0)
	v_cvt_pk_bf16_f32 v1, v2, v3
	s_nop 1
	ds_read2_b32 v[2:3], v7 offset0:134 offset1:199
	v_ashrrev_i32_e32 v7, 31, v6
	v_lshlrev_b64 v[6:7], 12, v[6:7]
	v_lshl_add_u64 v[4:5], v[4:5], 0, v[6:7]
	s_waitcnt lgkmcnt(0)
	v_cvt_pk_bf16_f32 v2, v2, v3
	s_nop 1
	global_store_dword v[4:5], v8, off
